# GEMM mainloops: LDS-DMA via SGPR base + precomputed VGPR offsets (no per-step 64-bit VALU address math), fewer ds_read address VALU ops, single M0 write per step
# speedup vs baseline: 1.0589x; 1.0408x over previous
; #define WAIT_V(n) asm volatile("s_waitcnt vmcnt(" #n ")" ::: "memory")
; #define BAR0() do { asm volatile("" ::: "memory"); __builtin_amdgcn_s_barrier(); asm volatile("" ::: "memory"); } while (0)
; template <class PF, class EF>
; DI void gemm_stream(int lda, int ldw, int K, unsigned char* smem, PF ptrs, EF epi) {
;     ...
;   H_DMA(sbase); ap += 64; bp += 64;
;   H_DMA(sbase + SLOT); ap += 64; bp += 64;
;   for (int it = 0;; ++it) {
;     f32x16 acc[4][2];
; #pragma unroll
;     for (int a = 0; a < 4; ++a)
; #pragma unroll
;       for (int b = 0; b < 2; ++b) zero16(acc[a][b]);
;     H_DMA(sbase + 2 * SLOT); ap += 64; bp += 64;
;     WAIT_V(4);
;     BAR0();
;     if (wm == 1) BAR0();
.LBB0_219:
	s_or_b64 exec, exec, s[6:7]
	v_mov_b32_e32 v64, 0
	v_lshl_add_u64 v[184:185], v[184:185], 0, 64
	v_lshl_add_u64 v[186:187], v[186:187], 0, 64
	v_cndmask_b32_e64 v196, v184, v186, s[0:1]
	v_cndmask_b32_e64 v197, v185, v187, s[0:1]
	s_nop 1
	v_readfirstlane_b32 s90, v196
	v_readfirstlane_b32 s91, v197
	v_add_u32_e32 v196, 0x1000, v182
	v_add_u32_e32 v197, s18, v182
	v_add_u32_e32 v198, s20, v182
	v_add_u32_e32 v199, s18, v198
	v_add_u32_e32 v197, 0xc00, v197
	v_add_u32_e32 v198, 0x800, v198
	v_add_u32_e32 v199, 0x400, v199
	s_sub_u32 s90, s90, 0x1000
	s_subb_u32 s91, s91, 0
	v_add_u32_e32 v200, v193, v181
	v_add_u32_e32 v201, v193, v192
	v_add_u32_e32 v202, v194, v181
	v_add_u32_e32 v203, v194, v192
	s_mov_b32 s13, 0
	s_mov_b32 s14, 0
	v_mov_b32_e32 v65, v64
	v_mov_b32_e32 v66, v64
	v_mov_b32_e32 v67, v64
	v_mov_b32_e32 v68, v64
	v_mov_b32_e32 v69, v64
	v_mov_b32_e32 v70, v64
	v_mov_b32_e32 v71, v64
	v_mov_b32_e32 v72, v64
	v_mov_b32_e32 v73, v64
	v_mov_b32_e32 v74, v64
	v_mov_b32_e32 v75, v64
	v_mov_b32_e32 v76, v64
	v_mov_b32_e32 v77, v64
	v_mov_b32_e32 v78, v64
	v_mov_b32_e32 v79, v64
	v_mov_b32_e32 v96, v64
	v_mov_b32_e32 v97, v64
	v_mov_b32_e32 v98, v64
	v_mov_b32_e32 v99, v64
	v_mov_b32_e32 v100, v64
	v_mov_b32_e32 v101, v64
	v_mov_b32_e32 v102, v64
	v_mov_b32_e32 v103, v64
	v_mov_b32_e32 v104, v64
	v_mov_b32_e32 v105, v64
	v_mov_b32_e32 v106, v64
	v_mov_b32_e32 v107, v64
	v_mov_b32_e32 v108, v64
	v_mov_b32_e32 v109, v64
	v_mov_b32_e32 v110, v64
	v_mov_b32_e32 v111, v64
	v_mov_b32_e32 v80, v64
	v_mov_b32_e32 v81, v64
	v_mov_b32_e32 v82, v64
	v_mov_b32_e32 v83, v64
	v_mov_b32_e32 v84, v64
	v_mov_b32_e32 v85, v64
	v_mov_b32_e32 v86, v64
	v_mov_b32_e32 v87, v64
	v_mov_b32_e32 v88, v64
	v_mov_b32_e32 v89, v64
	v_mov_b32_e32 v90, v64
	v_mov_b32_e32 v91, v64
	v_mov_b32_e32 v92, v64
	v_mov_b32_e32 v93, v64
	v_mov_b32_e32 v94, v64
	v_mov_b32_e32 v95, v64
	v_mov_b32_e32 v112, v64
	v_mov_b32_e32 v113, v64
	v_mov_b32_e32 v114, v64
	v_mov_b32_e32 v115, v64
	v_mov_b32_e32 v116, v64
	v_mov_b32_e32 v117, v64
	v_mov_b32_e32 v118, v64
	v_mov_b32_e32 v119, v64
	v_mov_b32_e32 v120, v64
	v_mov_b32_e32 v121, v64
	v_mov_b32_e32 v122, v64
	v_mov_b32_e32 v123, v64
	v_mov_b32_e32 v124, v64
	v_mov_b32_e32 v125, v64
	v_mov_b32_e32 v126, v64
	v_mov_b32_e32 v127, v64
	v_mov_b32_e32 v0, v64
	v_mov_b32_e32 v1, v64
	v_mov_b32_e32 v2, v64
	v_mov_b32_e32 v3, v64
	v_mov_b32_e32 v4, v64
	v_mov_b32_e32 v5, v64
	v_mov_b32_e32 v6, v64
	v_mov_b32_e32 v7, v64
	v_mov_b32_e32 v8, v64
	v_mov_b32_e32 v9, v64
	v_mov_b32_e32 v10, v64
	v_mov_b32_e32 v11, v64
	v_mov_b32_e32 v12, v64
	v_mov_b32_e32 v13, v64
	v_mov_b32_e32 v14, v64
	v_mov_b32_e32 v15, v64
	v_mov_b32_e32 v32, v64
	v_mov_b32_e32 v33, v64
	v_mov_b32_e32 v34, v64
	v_mov_b32_e32 v35, v64
	v_mov_b32_e32 v36, v64
	v_mov_b32_e32 v37, v64
	v_mov_b32_e32 v38, v64
	v_mov_b32_e32 v39, v64
	v_mov_b32_e32 v40, v64
	v_mov_b32_e32 v41, v64
	v_mov_b32_e32 v42, v64
	v_mov_b32_e32 v43, v64
	v_mov_b32_e32 v44, v64
	v_mov_b32_e32 v45, v64
	v_mov_b32_e32 v46, v64
	v_mov_b32_e32 v47, v64
	v_mov_b32_e32 v16, v64
	v_mov_b32_e32 v17, v64
	v_mov_b32_e32 v18, v64
	v_mov_b32_e32 v19, v64
	v_mov_b32_e32 v20, v64
	v_mov_b32_e32 v21, v64
	v_mov_b32_e32 v22, v64
	v_mov_b32_e32 v23, v64
	v_mov_b32_e32 v24, v64
	v_mov_b32_e32 v25, v64
	v_mov_b32_e32 v26, v64
	v_mov_b32_e32 v27, v64
	v_mov_b32_e32 v28, v64
	v_mov_b32_e32 v29, v64
	v_mov_b32_e32 v30, v64
	v_mov_b32_e32 v31, v64
	v_mov_b32_e32 v48, v64
	v_mov_b32_e32 v49, v64
	v_mov_b32_e32 v50, v64
	v_mov_b32_e32 v51, v64
	v_mov_b32_e32 v52, v64
	v_mov_b32_e32 v53, v64
	v_mov_b32_e32 v54, v64
	v_mov_b32_e32 v55, v64
	v_mov_b32_e32 v56, v64
	v_mov_b32_e32 v57, v64
	v_mov_b32_e32 v58, v64
	v_mov_b32_e32 v59, v64
	v_mov_b32_e32 v60, v64
	v_mov_b32_e32 v61, v64
	v_mov_b32_e32 v62, v64
	v_mov_b32_e32 v63, v64
	s_branch .LBB0_221

; template <class PF, class EF>
; DI void gemm_stream(int lda, int ldw, int K, unsigned char* smem, PF ptrs, EF epi) {
;     ...
;     for (int hh = 0; hh < nh; ++hh) {
;       bf16x8 fa[2][4], fb[2][2];
;       const int rem = nh - 2 - hh;
;       H_READ(sbase + rs * SLOT);
;       if (hh + 3 < nh) { H_DMA(sbase + ((rs + 3) & 3) * SLOT); ap += 64; bp += 64; }
.LBB0_221:
	s_lshl_b32 s8, s13, 15
	v_add_u32_e32 v129, s8, v200
	v_add_u32_e32 v128, s8, v201
	ds_read_b128 v[164:167], v129 offset:64
	ds_read_b128 v[160:163], v129 offset:2112
	ds_read_b128 v[140:143], v128 offset:64
	ds_read_b128 v[132:135], v128 offset:2112
	ds_read_b128 v[156:159], v129 offset:4160
	ds_read_b128 v[152:155], v129 offset:6208
	ds_read_b128 v[136:139], v128 offset:4160
	ds_read_b128 v[128:131], v128 offset:6208
	v_add_u32_e32 v145, s8, v202
	v_add_u32_e32 v144, s8, v203
	ds_read_b128 v[168:171], v145 offset:16448
	ds_read_b128 v[172:175], v145 offset:18496
	ds_read_b128 v[148:151], v144 offset:16448
	ds_read_b128 v[144:147], v144 offset:18496
	s_cmp_gt_u32 s14, 28
	s_cselect_b64 s[6:7], -1, 0
	s_and_b64 vcc, exec, s[6:7]
	s_cbranch_vccnz .LBB0_223
	s_add_i32 s8, s8, 0x18000
	s_and_b32 s8, s8, 0x18000
	s_add_i32 s8, s50, s8
	s_add_i32 m0, s8, 64
	s_nop 0
	global_load_lds_dwordx4 v196, s[90:91]
	global_load_lds_dwordx4 v197, s[90:91] offset:1024
	global_load_lds_dwordx4 v198, s[90:91] offset:2048
	global_load_lds_dwordx4 v199, s[90:91] offset:3072
	s_add_u32 s90, s90, 64
	s_addc_u32 s91, s91, 0

; #define WAIT_V(n) asm volatile("s_waitcnt vmcnt(" #n ")" ::: "memory")
; #define BAR0() do { asm volatile("" ::: "memory"); __builtin_amdgcn_s_barrier(); asm volatile("" ::: "memory"); } while (0)
; template <class PF, class EF>
; DI void gemm_stream(int lda, int ldw, int K, unsigned char* smem, PF ptrs, EF epi) {
;     ...
;   H_DMA(sbase); ap += 64; bp += 64;
;   H_DMA(sbase + SLOT); ap += 64; bp += 64;
;   for (int it = 0;; ++it) {
;     f32x16 acc[4][2];
; #pragma unroll
;     for (int a = 0; a < 4; ++a)
; #pragma unroll
;       for (int b = 0; b < 2; ++b) zero16(acc[a][b]);
;     H_DMA(sbase + 2 * SLOT); ap += 64; bp += 64;
;     WAIT_V(4);
;     BAR0();
;     if (wm == 1) BAR0();
.LBB0_613:
	s_or_b64 exec, exec, s[6:7]
	s_waitcnt vmcnt(0)
	v_mov_b32_e32 v96, 0
	v_lshl_add_u64 v[182:183], v[182:183], 0, 64
	v_lshl_add_u64 v[184:185], v[184:185], 0, 64
	v_cndmask_b32_e64 v194, v182, v184, s[0:1]
	v_cndmask_b32_e64 v195, v183, v185, s[0:1]
	s_nop 1
	v_readfirstlane_b32 s90, v194
	v_readfirstlane_b32 s91, v195
	v_add_u32_e32 v194, 0x1000, v178
	v_add_u32_e32 v195, s8, v178
	v_add_u32_e32 v196, s10, v178
	v_add_u32_e32 v197, s8, v196
	v_add_u32_e32 v195, 0xc00, v195
	v_add_u32_e32 v196, 0x800, v196
	v_add_u32_e32 v197, 0x400, v197
	s_sub_u32 s90, s90, 0x1000
	s_subb_u32 s91, s91, 0
	v_add_u32_e32 v198, v191, v181
	v_add_u32_e32 v199, v191, v190
	v_add_u32_e32 v200, v192, v181
	v_add_u32_e32 v201, v192, v190
	s_mov_b32 s34, 0
	s_mov_b32 s35, 0
	v_mov_b32_e32 v97, v96
	v_mov_b32_e32 v98, v96
	v_mov_b32_e32 v99, v96
	v_mov_b32_e32 v100, v96
	v_mov_b32_e32 v101, v96
	v_mov_b32_e32 v102, v96
	v_mov_b32_e32 v103, v96
	v_mov_b32_e32 v104, v96
	v_mov_b32_e32 v105, v96
	v_mov_b32_e32 v106, v96
	v_mov_b32_e32 v107, v96
	v_mov_b32_e32 v108, v96
	v_mov_b32_e32 v109, v96
	v_mov_b32_e32 v110, v96
	v_mov_b32_e32 v111, v96
	v_mov_b32_e32 v112, v96
	v_mov_b32_e32 v113, v96
	v_mov_b32_e32 v114, v96
	v_mov_b32_e32 v115, v96
	v_mov_b32_e32 v116, v96
	v_mov_b32_e32 v117, v96
	v_mov_b32_e32 v118, v96
	v_mov_b32_e32 v119, v96
	v_mov_b32_e32 v120, v96
	v_mov_b32_e32 v121, v96
	v_mov_b32_e32 v122, v96
	v_mov_b32_e32 v123, v96
	v_mov_b32_e32 v124, v96
	v_mov_b32_e32 v125, v96
	v_mov_b32_e32 v126, v96
	v_mov_b32_e32 v127, v96
	v_mov_b32_e32 v64, v96
	v_mov_b32_e32 v65, v96
	v_mov_b32_e32 v66, v96
	v_mov_b32_e32 v67, v96
	v_mov_b32_e32 v68, v96
	v_mov_b32_e32 v69, v96
	v_mov_b32_e32 v70, v96
	v_mov_b32_e32 v71, v96
	v_mov_b32_e32 v72, v96
	v_mov_b32_e32 v73, v96
	v_mov_b32_e32 v74, v96
	v_mov_b32_e32 v75, v96
	v_mov_b32_e32 v76, v96
	v_mov_b32_e32 v77, v96
	v_mov_b32_e32 v78, v96
	v_mov_b32_e32 v79, v96
	v_mov_b32_e32 v80, v96
	v_mov_b32_e32 v81, v96
	v_mov_b32_e32 v82, v96
	v_mov_b32_e32 v83, v96
	v_mov_b32_e32 v84, v96
	v_mov_b32_e32 v85, v96
	v_mov_b32_e32 v86, v96
	v_mov_b32_e32 v87, v96
	v_mov_b32_e32 v88, v96
	v_mov_b32_e32 v89, v96
	v_mov_b32_e32 v90, v96
	v_mov_b32_e32 v91, v96
	v_mov_b32_e32 v92, v96
	v_mov_b32_e32 v93, v96
	v_mov_b32_e32 v94, v96
	v_mov_b32_e32 v95, v96
	v_mov_b32_e32 v32, v96
	v_mov_b32_e32 v33, v96
	v_mov_b32_e32 v34, v96
	v_mov_b32_e32 v35, v96
	v_mov_b32_e32 v36, v96
	v_mov_b32_e32 v37, v96
	v_mov_b32_e32 v38, v96
	v_mov_b32_e32 v39, v96
	v_mov_b32_e32 v40, v96
	v_mov_b32_e32 v41, v96
	v_mov_b32_e32 v42, v96
	v_mov_b32_e32 v43, v96
	v_mov_b32_e32 v44, v96
	v_mov_b32_e32 v45, v96
	v_mov_b32_e32 v46, v96
	v_mov_b32_e32 v47, v96
	v_mov_b32_e32 v48, v96
	v_mov_b32_e32 v49, v96
	v_mov_b32_e32 v50, v96
	v_mov_b32_e32 v51, v96
	v_mov_b32_e32 v52, v96
	v_mov_b32_e32 v53, v96
	v_mov_b32_e32 v54, v96
	v_mov_b32_e32 v55, v96
	v_mov_b32_e32 v56, v96
	v_mov_b32_e32 v57, v96
	v_mov_b32_e32 v58, v96
	v_mov_b32_e32 v59, v96
	v_mov_b32_e32 v60, v96
	v_mov_b32_e32 v61, v96
	v_mov_b32_e32 v62, v96
	v_mov_b32_e32 v63, v96
	v_mov_b32_e32 v0, v96
	v_mov_b32_e32 v1, v96
	v_mov_b32_e32 v2, v96
	v_mov_b32_e32 v3, v96
	v_mov_b32_e32 v4, v96
	v_mov_b32_e32 v5, v96
	v_mov_b32_e32 v6, v96
	v_mov_b32_e32 v7, v96
	v_mov_b32_e32 v8, v96
	v_mov_b32_e32 v9, v96
	v_mov_b32_e32 v10, v96
	v_mov_b32_e32 v11, v96
	v_mov_b32_e32 v12, v96
	v_mov_b32_e32 v13, v96
	v_mov_b32_e32 v14, v96
	v_mov_b32_e32 v15, v96
	v_mov_b32_e32 v16, v96
	v_mov_b32_e32 v17, v96
	v_mov_b32_e32 v18, v96
	v_mov_b32_e32 v19, v96
	v_mov_b32_e32 v20, v96
	v_mov_b32_e32 v21, v96
	v_mov_b32_e32 v22, v96
	v_mov_b32_e32 v23, v96
	v_mov_b32_e32 v24, v96
	v_mov_b32_e32 v25, v96
	v_mov_b32_e32 v26, v96
	v_mov_b32_e32 v27, v96
	v_mov_b32_e32 v28, v96
	v_mov_b32_e32 v29, v96
	v_mov_b32_e32 v30, v96
	v_mov_b32_e32 v31, v96
	s_branch .LBB0_615

; template <class PF, class EF>
; DI void gemm_stream(int lda, int ldw, int K, unsigned char* smem, PF ptrs, EF epi) {
;     ...
;     for (int hh = 0; hh < nh; ++hh) {
;       bf16x8 fa[2][4], fb[2][2];
;       const int rem = nh - 2 - hh;
;       H_READ(sbase + rs * SLOT);
;       if (hh + 3 < nh) { H_DMA(sbase + ((rs + 3) & 3) * SLOT); ap += 64; bp += 64; }
.LBB0_615:
	s_lshl_b32 s16, s34, 15
	v_add_u32_e32 v129, s16, v198
	v_add_u32_e32 v128, s16, v199
	ds_read_b128 v[164:167], v129 offset:64
	ds_read_b128 v[160:163], v129 offset:2112
	ds_read_b128 v[140:143], v128 offset:64
	ds_read_b128 v[132:135], v128 offset:2112
	ds_read_b128 v[156:159], v129 offset:4160
	ds_read_b128 v[152:155], v129 offset:6208
	ds_read_b128 v[136:139], v128 offset:4160
	ds_read_b128 v[128:131], v128 offset:6208
	v_add_u32_e32 v145, s16, v200
	v_add_u32_e32 v144, s16, v201
	ds_read_b128 v[168:171], v145 offset:16448
	ds_read_b128 v[172:175], v145 offset:18496
	ds_read_b128 v[148:151], v144 offset:16448
	ds_read_b128 v[144:147], v144 offset:18496
	s_cmp_gt_u32 s35, 12
	s_cselect_b64 s[6:7], -1, 0
	s_and_b64 vcc, exec, s[6:7]
	s_cbranch_vccnz .LBB0_617
	s_add_i32 s16, s16, 0x18000
	s_and_b32 s16, s16, 0x18000
	s_add_i32 s16, s20, s16
	s_add_i32 m0, s16, 64
	s_nop 0
	global_load_lds_dwordx4 v194, s[90:91]
	global_load_lds_dwordx4 v195, s[90:91] offset:1024
	global_load_lds_dwordx4 v196, s[90:91] offset:2048
	global_load_lds_dwordx4 v197, s[90:91] offset:3072
	s_add_u32 s90, s90, 64
	s_addc_u32 s91, s91, 0

; #define WAIT_V(n) asm volatile("s_waitcnt vmcnt(" #n ")" ::: "memory")
; #define BAR0() do { asm volatile("" ::: "memory"); __builtin_amdgcn_s_barrier(); asm volatile("" ::: "memory"); } while (0)
; template <class PF, class EF>
; DI void gemm_stream(int lda, int ldw, int K, unsigned char* smem, PF ptrs, EF epi) {
;     ...
;   H_DMA(sbase); ap += 64; bp += 64;
;   H_DMA(sbase + SLOT); ap += 64; bp += 64;
;   for (int it = 0;; ++it) {
;     f32x16 acc[4][2];
; #pragma unroll
;     for (int a = 0; a < 4; ++a)
; #pragma unroll
;       for (int b = 0; b < 2; ++b) zero16(acc[a][b]);
;     H_DMA(sbase + 2 * SLOT); ap += 64; bp += 64;
;     WAIT_V(4);
;     BAR0();
;     if (wm == 1) BAR0();
.LBB0_679:
	s_or_b64 exec, exec, s[8:9]
	s_waitcnt vmcnt(0)
	v_mov_b32_e32 v96, 0
	v_lshl_add_u64 v[186:187], v[186:187], 0, 64
	v_lshl_add_u64 v[188:189], v[188:189], 0, 64
	v_cndmask_b32_e64 v196, v186, v188, s[2:3]
	v_cndmask_b32_e64 v197, v187, v189, s[2:3]
	s_nop 1
	v_readfirstlane_b32 s90, v196
	v_readfirstlane_b32 s91, v197
	v_add_u32_e32 v196, 0x1000, v182
	v_add_u32_e32 v197, s22, v182
	v_add_u32_e32 v198, s20, v182
	v_add_u32_e32 v199, s22, v198
	v_add_u32_e32 v197, 0xc00, v197
	v_add_u32_e32 v198, 0x800, v198
	v_add_u32_e32 v199, 0x400, v199
	s_sub_u32 s90, s90, 0x1000
	s_subb_u32 s91, s91, 0
	v_add_u32_e32 v200, v193, v181
	v_add_u32_e32 v201, v193, v192
	v_add_u32_e32 v202, v194, v181
	v_add_u32_e32 v203, v194, v192
	s_mov_b32 s38, 0
	s_mov_b32 s39, 0
	v_mov_b32_e32 v97, v96
	v_mov_b32_e32 v98, v96
	v_mov_b32_e32 v99, v96
	v_mov_b32_e32 v100, v96
	v_mov_b32_e32 v101, v96
	v_mov_b32_e32 v102, v96
	v_mov_b32_e32 v103, v96
	v_mov_b32_e32 v104, v96
	v_mov_b32_e32 v105, v96
	v_mov_b32_e32 v106, v96
	v_mov_b32_e32 v107, v96
	v_mov_b32_e32 v108, v96
	v_mov_b32_e32 v109, v96
	v_mov_b32_e32 v110, v96
	v_mov_b32_e32 v111, v96
	v_mov_b32_e32 v112, v96
	v_mov_b32_e32 v113, v96
	v_mov_b32_e32 v114, v96
	v_mov_b32_e32 v115, v96
	v_mov_b32_e32 v116, v96
	v_mov_b32_e32 v117, v96
	v_mov_b32_e32 v118, v96
	v_mov_b32_e32 v119, v96
	v_mov_b32_e32 v120, v96
	v_mov_b32_e32 v121, v96
	v_mov_b32_e32 v122, v96
	v_mov_b32_e32 v123, v96
	v_mov_b32_e32 v124, v96
	v_mov_b32_e32 v125, v96
	v_mov_b32_e32 v126, v96
	v_mov_b32_e32 v127, v96
	v_mov_b32_e32 v64, v96
	v_mov_b32_e32 v65, v96
	v_mov_b32_e32 v66, v96
	v_mov_b32_e32 v67, v96
	v_mov_b32_e32 v68, v96
	v_mov_b32_e32 v69, v96
	v_mov_b32_e32 v70, v96
	v_mov_b32_e32 v71, v96
	v_mov_b32_e32 v72, v96
	v_mov_b32_e32 v73, v96
	v_mov_b32_e32 v74, v96
	v_mov_b32_e32 v75, v96
	v_mov_b32_e32 v76, v96
	v_mov_b32_e32 v77, v96
	v_mov_b32_e32 v78, v96
	v_mov_b32_e32 v79, v96
	v_mov_b32_e32 v80, v96
	v_mov_b32_e32 v81, v96
	v_mov_b32_e32 v82, v96
	v_mov_b32_e32 v83, v96
	v_mov_b32_e32 v84, v96
	v_mov_b32_e32 v85, v96
	v_mov_b32_e32 v86, v96
	v_mov_b32_e32 v87, v96
	v_mov_b32_e32 v88, v96
	v_mov_b32_e32 v89, v96
	v_mov_b32_e32 v90, v96
	v_mov_b32_e32 v91, v96
	v_mov_b32_e32 v92, v96
	v_mov_b32_e32 v93, v96
	v_mov_b32_e32 v94, v96
	v_mov_b32_e32 v95, v96
	v_mov_b32_e32 v32, v96
	v_mov_b32_e32 v33, v96
	v_mov_b32_e32 v34, v96
	v_mov_b32_e32 v35, v96
	v_mov_b32_e32 v36, v96
	v_mov_b32_e32 v37, v96
	v_mov_b32_e32 v38, v96
	v_mov_b32_e32 v39, v96
	v_mov_b32_e32 v40, v96
	v_mov_b32_e32 v41, v96
	v_mov_b32_e32 v42, v96
	v_mov_b32_e32 v43, v96
	v_mov_b32_e32 v44, v96
	v_mov_b32_e32 v45, v96
	v_mov_b32_e32 v46, v96
	v_mov_b32_e32 v47, v96
	v_mov_b32_e32 v48, v96
	v_mov_b32_e32 v49, v96
	v_mov_b32_e32 v50, v96
	v_mov_b32_e32 v51, v96
	v_mov_b32_e32 v52, v96
	v_mov_b32_e32 v53, v96
	v_mov_b32_e32 v54, v96
	v_mov_b32_e32 v55, v96
	v_mov_b32_e32 v56, v96
	v_mov_b32_e32 v57, v96
	v_mov_b32_e32 v58, v96
	v_mov_b32_e32 v59, v96
	v_mov_b32_e32 v60, v96
	v_mov_b32_e32 v61, v96
	v_mov_b32_e32 v62, v96
	v_mov_b32_e32 v63, v96
	v_mov_b32_e32 v0, v96
	v_mov_b32_e32 v1, v96
	v_mov_b32_e32 v2, v96
	v_mov_b32_e32 v3, v96
	v_mov_b32_e32 v4, v96
	v_mov_b32_e32 v5, v96
	v_mov_b32_e32 v6, v96
	v_mov_b32_e32 v7, v96
	v_mov_b32_e32 v8, v96
	v_mov_b32_e32 v9, v96
	v_mov_b32_e32 v10, v96
	v_mov_b32_e32 v11, v96
	v_mov_b32_e32 v12, v96
	v_mov_b32_e32 v13, v96
	v_mov_b32_e32 v14, v96
	v_mov_b32_e32 v15, v96
	v_mov_b32_e32 v16, v96
	v_mov_b32_e32 v17, v96
	v_mov_b32_e32 v18, v96
	v_mov_b32_e32 v19, v96
	v_mov_b32_e32 v20, v96
	v_mov_b32_e32 v21, v96
	v_mov_b32_e32 v22, v96
	v_mov_b32_e32 v23, v96
	v_mov_b32_e32 v24, v96
	v_mov_b32_e32 v25, v96
	v_mov_b32_e32 v26, v96
	v_mov_b32_e32 v27, v96
	v_mov_b32_e32 v28, v96
	v_mov_b32_e32 v29, v96
	v_mov_b32_e32 v30, v96
	v_mov_b32_e32 v31, v96
	s_branch .LBB0_681

; template <class PF, class EF>
; DI void gemm_stream(int lda, int ldw, int K, unsigned char* smem, PF ptrs, EF epi) {
;     ...
;     for (int hh = 0; hh < nh; ++hh) {
;       bf16x8 fa[2][4], fb[2][2];
;       const int rem = nh - 2 - hh;
;       H_READ(sbase + rs * SLOT);
;       if (hh + 3 < nh) { H_DMA(sbase + ((rs + 3) & 3) * SLOT); ap += 64; bp += 64; }
.LBB0_681:
	s_lshl_b32 s10, s38, 15
	v_add_u32_e32 v129, s10, v200
	v_add_u32_e32 v128, s10, v201
	ds_read_b128 v[164:167], v129 offset:64
	ds_read_b128 v[160:163], v129 offset:2112
	ds_read_b128 v[140:143], v128 offset:64
	ds_read_b128 v[132:135], v128 offset:2112
	ds_read_b128 v[156:159], v129 offset:4160
	ds_read_b128 v[152:155], v129 offset:6208
	ds_read_b128 v[136:139], v128 offset:4160
	ds_read_b128 v[128:131], v128 offset:6208
	v_add_u32_e32 v145, s10, v202
	v_add_u32_e32 v144, s10, v203
	ds_read_b128 v[168:171], v145 offset:16448
	ds_read_b128 v[172:175], v145 offset:18496
	ds_read_b128 v[148:151], v144 offset:16448
	ds_read_b128 v[144:147], v144 offset:18496
	s_cmp_gt_u32 s39, 28
	s_cselect_b64 s[8:9], -1, 0
	s_and_b64 vcc, exec, s[8:9]
	s_cbranch_vccnz .LBB0_683
	s_add_i32 s10, s10, 0x18000
	s_and_b32 s10, s10, 0x18000
	s_add_i32 s10, s26, s10
	s_add_i32 m0, s10, 64
	s_nop 0
	global_load_lds_dwordx4 v196, s[90:91]
	global_load_lds_dwordx4 v197, s[90:91] offset:1024
	global_load_lds_dwordx4 v198, s[90:91] offset:2048
	global_load_lds_dwordx4 v199, s[90:91] offset:3072
	s_add_u32 s90, s90, 64
	s_addc_u32 s91, s91, 0

; template <class PF, class EF>
; DI void gemm_stream(int lda, int ldw, int K, unsigned char* smem, PF ptrs, EF epi) {
;     ...
;   const int c0 = (h ^ ((r >> 2) & 3)) * 16, c1 = c0 ^ 32;
;   const int aoff = (wm * 128 + r) * 64, boff = (256 + wn * 64 + r) * 64;
;   const int lr16 = lane >> 2, lchunk = (lane & 3) ^ ((lane >> 4) & 3);
;   const int wu = __builtin_amdgcn_readfirstlane(w);
;   const bool isB = wu >= 4;
;   const unsigned goff = isB ? (unsigned)((((wu - 4) * 64 + 2 * lr16) * ldw + lchunk * 8) * 2)
;                             : (unsigned)(((wu * 64 + lr16) * lda + lchunk * 8) * 2);
;   const unsigned st1 = isB ? (unsigned)(32 * ldw * 2) : (unsigned)(16 * lda * 2);
;   const unsigned st2 = isB ? (unsigned)(1 * ldw * 2) : (unsigned)(32 * lda * 2);
;     ...
;   const char *ap, *bp;
;   {
;     const u16 *ta, *tb;
;     int it0 = 0;
;     asm volatile("" : "+s"(it0));
;     if (!ptrs(it0, ta, tb)) return;
;     ap = (const char*)ta; bp = (const char*)tb;
;   }
;   H_DMA(sbase); ap += 64; bp += 64;
;   H_DMA(sbase + SLOT); ap += 64; bp += 64;
;   for (int it = 0;; ++it) {
;     f32x16 acc[4][2];
; #pragma unroll
;     for (int a = 0; a < 4; ++a)
; #pragma unroll
;       for (int b = 0; b < 2; ++b) zero16(acc[a][b]);
;     H_DMA(sbase + 2 * SLOT); ap += 64; bp += 64;
.LBB0_796:
	s_or_b64 exec, exec, s[8:9]
	v_mov_b32_e32 v96, 0
	v_lshl_add_u64 v[184:185], v[184:185], 0, 64
	v_lshl_add_u64 v[186:187], v[186:187], 0, 64
	v_cndmask_b32_e64 v196, v184, v186, s[2:3]
	v_cndmask_b32_e64 v197, v185, v187, s[2:3]
	s_nop 1
	v_readfirstlane_b32 s90, v196
	v_readfirstlane_b32 s91, v197
	v_add_u32_e32 v196, 0x1000, v182
	v_add_u32_e32 v197, s20, v182
	v_add_u32_e32 v198, s22, v182
	v_add_u32_e32 v199, s20, v198
	v_add_u32_e32 v197, 0xc00, v197
	v_add_u32_e32 v198, 0x800, v198
	v_add_u32_e32 v199, 0x400, v199
	s_sub_u32 s90, s90, 0x1000
	s_subb_u32 s91, s91, 0
	v_add_u32_e32 v200, v193, v181
	v_add_u32_e32 v201, v193, v192
	v_add_u32_e32 v202, v194, v181
	v_add_u32_e32 v203, v194, v192
	s_mov_b32 s43, 0
	s_mov_b32 s44, 0
	v_mov_b32_e32 v97, v96
	v_mov_b32_e32 v98, v96
	v_mov_b32_e32 v99, v96
	v_mov_b32_e32 v100, v96
	v_mov_b32_e32 v101, v96
	v_mov_b32_e32 v102, v96
	v_mov_b32_e32 v103, v96
	v_mov_b32_e32 v104, v96
	v_mov_b32_e32 v105, v96
	v_mov_b32_e32 v106, v96
	v_mov_b32_e32 v107, v96
	v_mov_b32_e32 v108, v96
	v_mov_b32_e32 v109, v96
	v_mov_b32_e32 v110, v96
	v_mov_b32_e32 v111, v96
	v_mov_b32_e32 v112, v96
	v_mov_b32_e32 v113, v96
	v_mov_b32_e32 v114, v96
	v_mov_b32_e32 v115, v96
	v_mov_b32_e32 v116, v96
	v_mov_b32_e32 v117, v96
	v_mov_b32_e32 v118, v96
	v_mov_b32_e32 v119, v96
	v_mov_b32_e32 v120, v96
	v_mov_b32_e32 v121, v96
	v_mov_b32_e32 v122, v96
	v_mov_b32_e32 v123, v96
	v_mov_b32_e32 v124, v96
	v_mov_b32_e32 v125, v96
	v_mov_b32_e32 v126, v96
	v_mov_b32_e32 v127, v96
	v_mov_b32_e32 v64, v96
	v_mov_b32_e32 v65, v96
	v_mov_b32_e32 v66, v96
	v_mov_b32_e32 v67, v96
	v_mov_b32_e32 v68, v96
	v_mov_b32_e32 v69, v96
	v_mov_b32_e32 v70, v96
	v_mov_b32_e32 v71, v96
	v_mov_b32_e32 v72, v96
	v_mov_b32_e32 v73, v96
	v_mov_b32_e32 v74, v96
	v_mov_b32_e32 v75, v96
	v_mov_b32_e32 v76, v96
	v_mov_b32_e32 v77, v96
	v_mov_b32_e32 v78, v96
	v_mov_b32_e32 v79, v96
	v_mov_b32_e32 v80, v96
	v_mov_b32_e32 v81, v96
	v_mov_b32_e32 v82, v96
	v_mov_b32_e32 v83, v96
	v_mov_b32_e32 v84, v96
	v_mov_b32_e32 v85, v96
	v_mov_b32_e32 v86, v96
	v_mov_b32_e32 v87, v96
	v_mov_b32_e32 v88, v96
	v_mov_b32_e32 v89, v96
	v_mov_b32_e32 v90, v96
	v_mov_b32_e32 v91, v96
	v_mov_b32_e32 v92, v96
	v_mov_b32_e32 v93, v96
	v_mov_b32_e32 v94, v96
	v_mov_b32_e32 v95, v96
	v_mov_b32_e32 v32, v96
	v_mov_b32_e32 v33, v96
	v_mov_b32_e32 v34, v96
	v_mov_b32_e32 v35, v96
	v_mov_b32_e32 v36, v96
	v_mov_b32_e32 v37, v96
	v_mov_b32_e32 v38, v96
	v_mov_b32_e32 v39, v96
	v_mov_b32_e32 v40, v96
	v_mov_b32_e32 v41, v96
	v_mov_b32_e32 v42, v96
	v_mov_b32_e32 v43, v96
	v_mov_b32_e32 v44, v96
	v_mov_b32_e32 v45, v96
	v_mov_b32_e32 v46, v96
	v_mov_b32_e32 v47, v96
	v_mov_b32_e32 v48, v96
	v_mov_b32_e32 v49, v96
	v_mov_b32_e32 v50, v96
	v_mov_b32_e32 v51, v96
	v_mov_b32_e32 v52, v96
	v_mov_b32_e32 v53, v96
	v_mov_b32_e32 v54, v96
	v_mov_b32_e32 v55, v96
	v_mov_b32_e32 v56, v96
	v_mov_b32_e32 v57, v96
	v_mov_b32_e32 v58, v96
	v_mov_b32_e32 v59, v96
	v_mov_b32_e32 v60, v96
	v_mov_b32_e32 v61, v96
	v_mov_b32_e32 v62, v96
	v_mov_b32_e32 v63, v96
	v_mov_b32_e32 v0, v96
	v_mov_b32_e32 v1, v96
	v_mov_b32_e32 v2, v96
	v_mov_b32_e32 v3, v96
	v_mov_b32_e32 v4, v96
	v_mov_b32_e32 v5, v96
	v_mov_b32_e32 v6, v96
	v_mov_b32_e32 v7, v96
	v_mov_b32_e32 v8, v96
	v_mov_b32_e32 v9, v96
	v_mov_b32_e32 v10, v96
	v_mov_b32_e32 v11, v96
	v_mov_b32_e32 v12, v96
	v_mov_b32_e32 v13, v96
	v_mov_b32_e32 v14, v96
	v_mov_b32_e32 v15, v96
	v_mov_b32_e32 v16, v96
	v_mov_b32_e32 v17, v96
	v_mov_b32_e32 v18, v96
	v_mov_b32_e32 v19, v96
	v_mov_b32_e32 v20, v96
	v_mov_b32_e32 v21, v96
	v_mov_b32_e32 v22, v96
	v_mov_b32_e32 v23, v96
	v_mov_b32_e32 v24, v96
	v_mov_b32_e32 v25, v96
	v_mov_b32_e32 v26, v96
	v_mov_b32_e32 v27, v96
	v_mov_b32_e32 v28, v96
	v_mov_b32_e32 v29, v96
	v_mov_b32_e32 v30, v96
	v_mov_b32_e32 v31, v96
	s_branch .LBB0_798

; template <class PF, class EF>
; DI void gemm_stream(int lda, int ldw, int K, unsigned char* smem, PF ptrs, EF epi) {
;     ...
;     for (int hh = 0; hh < nh; ++hh) {
;       bf16x8 fa[2][4], fb[2][2];
;       const int rem = nh - 2 - hh;
;       H_READ(sbase + rs * SLOT);
;       if (hh + 3 < nh) { H_DMA(sbase + ((rs + 3) & 3) * SLOT); ap += 64; bp += 64; }
.LBB0_798:
	s_lshl_b32 s10, s43, 15
	v_add_u32_e32 v129, s10, v200
	v_add_u32_e32 v128, s10, v201
	ds_read_b128 v[164:167], v129 offset:64
	ds_read_b128 v[160:163], v129 offset:2112
	ds_read_b128 v[140:143], v128 offset:64
	ds_read_b128 v[132:135], v128 offset:2112
	ds_read_b128 v[156:159], v129 offset:4160
	ds_read_b128 v[152:155], v129 offset:6208
	ds_read_b128 v[136:139], v128 offset:4160
	ds_read_b128 v[128:131], v128 offset:6208
	v_add_u32_e32 v145, s10, v202
	v_add_u32_e32 v144, s10, v203
	ds_read_b128 v[168:171], v145 offset:16448
	ds_read_b128 v[172:175], v145 offset:18496
	ds_read_b128 v[148:151], v144 offset:16448
	ds_read_b128 v[144:147], v144 offset:18496
	s_cmp_gt_u32 s44, 28
	s_cselect_b64 s[8:9], -1, 0
	s_and_b64 vcc, exec, s[8:9]
	s_cbranch_vccnz .LBB0_800
	s_add_i32 s10, s10, 0x18000
	s_and_b32 s10, s10, 0x18000
	s_add_i32 s10, s15, s10
	s_add_i32 m0, s10, 64
	s_nop 0
	global_load_lds_dwordx4 v196, s[90:91]
	global_load_lds_dwordx4 v197, s[90:91] offset:1024
	global_load_lds_dwordx4 v198, s[90:91] offset:2048
	global_load_lds_dwordx4 v199, s[90:91] offset:3072
	s_add_u32 s90, s90, 64
	s_addc_u32 s91, s91, 0

; template <class PF, class EF>
; DI void gemm_stream(int lda, int ldw, int K, unsigned char* smem, PF ptrs, EF epi) {
;     ...
;   const int c0 = (h ^ ((r >> 2) & 3)) * 16, c1 = c0 ^ 32;
;   const int aoff = (wm * 128 + r) * 64, boff = (256 + wn * 64 + r) * 64;
;   const int lr16 = lane >> 2, lchunk = (lane & 3) ^ ((lane >> 4) & 3);
;   const int wu = __builtin_amdgcn_readfirstlane(w);
;   const bool isB = wu >= 4;
;   const unsigned goff = isB ? (unsigned)((((wu - 4) * 64 + 2 * lr16) * ldw + lchunk * 8) * 2)
;                             : (unsigned)(((wu * 64 + lr16) * lda + lchunk * 8) * 2);
;   const unsigned st1 = isB ? (unsigned)(32 * ldw * 2) : (unsigned)(16 * lda * 2);
;   const unsigned st2 = isB ? (unsigned)(1 * ldw * 2) : (unsigned)(32 * lda * 2);
;     ...
;   const char *ap, *bp;
;   {
;     const u16 *ta, *tb;
;     int it0 = 0;
;     asm volatile("" : "+s"(it0));
;     if (!ptrs(it0, ta, tb)) return;
;     ap = (const char*)ta; bp = (const char*)tb;
;   }
;   H_DMA(sbase); ap += 64; bp += 64;
;   H_DMA(sbase + SLOT); ap += 64; bp += 64;
;   for (int it = 0;; ++it) {
;     f32x16 acc[4][2];
; #pragma unroll
;     for (int a = 0; a < 4; ++a)
; #pragma unroll
;       for (int b = 0; b < 2; ++b) zero16(acc[a][b]);
;     H_DMA(sbase + 2 * SLOT); ap += 64; bp += 64;
.LBB0_842:
	s_or_b64 exec, exec, s[8:9]
	v_mov_b32_e32 v96, 0
	v_lshl_add_u64 v[184:185], v[184:185], 0, 64
	v_lshl_add_u64 v[188:189], v[188:189], 0, 64
	v_cndmask_b32_e64 v194, v184, v188, s[2:3]
	v_cndmask_b32_e64 v195, v185, v189, s[2:3]
	s_nop 1
	v_readfirstlane_b32 s90, v194
	v_readfirstlane_b32 s91, v195
	v_add_u32_e32 v194, 0x1000, v178
	v_add_u32_e32 v195, s24, v178
	v_add_u32_e32 v196, s22, v178
	v_add_u32_e32 v197, s24, v196
	v_add_u32_e32 v195, 0xc00, v195
	v_add_u32_e32 v196, 0x800, v196
	v_add_u32_e32 v197, 0x400, v197
	s_sub_u32 s90, s90, 0x1000
	s_subb_u32 s91, s91, 0
	v_add_u32_e32 v198, v191, v181
	v_add_u32_e32 v199, v191, v190
	v_add_u32_e32 v200, v192, v181
	v_add_u32_e32 v201, v192, v190
	s_mov_b32 s44, 0
	s_mov_b32 s45, 0
	v_mov_b32_e32 v97, v96
	v_mov_b32_e32 v98, v96
	v_mov_b32_e32 v99, v96
	v_mov_b32_e32 v100, v96
	v_mov_b32_e32 v101, v96
	v_mov_b32_e32 v102, v96
	v_mov_b32_e32 v103, v96
	v_mov_b32_e32 v104, v96
	v_mov_b32_e32 v105, v96
	v_mov_b32_e32 v106, v96
	v_mov_b32_e32 v107, v96
	v_mov_b32_e32 v108, v96
	v_mov_b32_e32 v109, v96
	v_mov_b32_e32 v110, v96
	v_mov_b32_e32 v111, v96
	v_mov_b32_e32 v112, v96
	v_mov_b32_e32 v113, v96
	v_mov_b32_e32 v114, v96
	v_mov_b32_e32 v115, v96
	v_mov_b32_e32 v116, v96
	v_mov_b32_e32 v117, v96
	v_mov_b32_e32 v118, v96
	v_mov_b32_e32 v119, v96
	v_mov_b32_e32 v120, v96
	v_mov_b32_e32 v121, v96
	v_mov_b32_e32 v122, v96
	v_mov_b32_e32 v123, v96
	v_mov_b32_e32 v124, v96
	v_mov_b32_e32 v125, v96
	v_mov_b32_e32 v126, v96
	v_mov_b32_e32 v127, v96
	v_mov_b32_e32 v64, v96
	v_mov_b32_e32 v65, v96
	v_mov_b32_e32 v66, v96
	v_mov_b32_e32 v67, v96
	v_mov_b32_e32 v68, v96
	v_mov_b32_e32 v69, v96
	v_mov_b32_e32 v70, v96
	v_mov_b32_e32 v71, v96
	v_mov_b32_e32 v72, v96
	v_mov_b32_e32 v73, v96
	v_mov_b32_e32 v74, v96
	v_mov_b32_e32 v75, v96
	v_mov_b32_e32 v76, v96
	v_mov_b32_e32 v77, v96
	v_mov_b32_e32 v78, v96
	v_mov_b32_e32 v79, v96
	v_mov_b32_e32 v80, v96
	v_mov_b32_e32 v81, v96
	v_mov_b32_e32 v82, v96
	v_mov_b32_e32 v83, v96
	v_mov_b32_e32 v84, v96
	v_mov_b32_e32 v85, v96
	v_mov_b32_e32 v86, v96
	v_mov_b32_e32 v87, v96
	v_mov_b32_e32 v88, v96
	v_mov_b32_e32 v89, v96
	v_mov_b32_e32 v90, v96
	v_mov_b32_e32 v91, v96
	v_mov_b32_e32 v92, v96
	v_mov_b32_e32 v93, v96
	v_mov_b32_e32 v94, v96
	v_mov_b32_e32 v95, v96
	v_mov_b32_e32 v32, v96
	v_mov_b32_e32 v33, v96
	v_mov_b32_e32 v34, v96
	v_mov_b32_e32 v35, v96
	v_mov_b32_e32 v36, v96
	v_mov_b32_e32 v37, v96
	v_mov_b32_e32 v38, v96
	v_mov_b32_e32 v39, v96
	v_mov_b32_e32 v40, v96
	v_mov_b32_e32 v41, v96
	v_mov_b32_e32 v42, v96
	v_mov_b32_e32 v43, v96
	v_mov_b32_e32 v44, v96
	v_mov_b32_e32 v45, v96
	v_mov_b32_e32 v46, v96
	v_mov_b32_e32 v47, v96
	v_mov_b32_e32 v48, v96
	v_mov_b32_e32 v49, v96
	v_mov_b32_e32 v50, v96
	v_mov_b32_e32 v51, v96
	v_mov_b32_e32 v52, v96
	v_mov_b32_e32 v53, v96
	v_mov_b32_e32 v54, v96
	v_mov_b32_e32 v55, v96
	v_mov_b32_e32 v56, v96
	v_mov_b32_e32 v57, v96
	v_mov_b32_e32 v58, v96
	v_mov_b32_e32 v59, v96
	v_mov_b32_e32 v60, v96
	v_mov_b32_e32 v61, v96
	v_mov_b32_e32 v62, v96
	v_mov_b32_e32 v63, v96
	v_mov_b32_e32 v0, v96
	v_mov_b32_e32 v1, v96
	v_mov_b32_e32 v2, v96
	v_mov_b32_e32 v3, v96
	v_mov_b32_e32 v4, v96
	v_mov_b32_e32 v5, v96
	v_mov_b32_e32 v6, v96
	v_mov_b32_e32 v7, v96
	v_mov_b32_e32 v8, v96
	v_mov_b32_e32 v9, v96
	v_mov_b32_e32 v10, v96
	v_mov_b32_e32 v11, v96
	v_mov_b32_e32 v12, v96
	v_mov_b32_e32 v13, v96
	v_mov_b32_e32 v14, v96
	v_mov_b32_e32 v15, v96
	v_mov_b32_e32 v16, v96
	v_mov_b32_e32 v17, v96
	v_mov_b32_e32 v18, v96
	v_mov_b32_e32 v19, v96
	s_waitcnt vmcnt(0)
	v_mov_b32_e32 v20, v96
	v_mov_b32_e32 v21, v96
	v_mov_b32_e32 v22, v96
	v_mov_b32_e32 v23, v96
	v_mov_b32_e32 v24, v96
	v_mov_b32_e32 v25, v96
	v_mov_b32_e32 v26, v96
	v_mov_b32_e32 v27, v96
	v_mov_b32_e32 v28, v96
	v_mov_b32_e32 v29, v96
	v_mov_b32_e32 v30, v96
	v_mov_b32_e32 v31, v96
	s_branch .LBB0_844

; template <class PF, class EF>
; DI void gemm_stream(int lda, int ldw, int K, unsigned char* smem, PF ptrs, EF epi) {
;     ...
;     for (int hh = 0; hh < nh; ++hh) {
;       bf16x8 fa[2][4], fb[2][2];
;       const int rem = nh - 2 - hh;
;       H_READ(sbase + rs * SLOT);
;       if (hh + 3 < nh) { H_DMA(sbase + ((rs + 3) & 3) * SLOT); ap += 64; bp += 64; }
.LBB0_844:
	s_lshl_b32 s28, s44, 15
	v_add_u32_e32 v129, s28, v198
	v_add_u32_e32 v128, s28, v199
	ds_read_b128 v[164:167], v129 offset:64
	ds_read_b128 v[160:163], v129 offset:2112
	ds_read_b128 v[140:143], v128 offset:64
	ds_read_b128 v[132:135], v128 offset:2112
	ds_read_b128 v[156:159], v129 offset:4160
	ds_read_b128 v[152:155], v129 offset:6208
	ds_read_b128 v[136:139], v128 offset:4160
	ds_read_b128 v[128:131], v128 offset:6208
	v_add_u32_e32 v145, s28, v200
	v_add_u32_e32 v144, s28, v201
	ds_read_b128 v[168:171], v145 offset:16448
	ds_read_b128 v[172:175], v145 offset:18496
	ds_read_b128 v[148:151], v144 offset:16448
	ds_read_b128 v[144:147], v144 offset:18496
	s_cmpk_gt_u32 s45, 0x54
	s_cselect_b64 s[8:9], -1, 0
	s_and_b64 vcc, exec, s[8:9]
	s_cbranch_vccnz .LBB0_846
	s_add_i32 s28, s28, 0x18000
	s_and_b32 s28, s28, 0x18000
	s_add_i32 s28, s34, s28
	s_add_i32 m0, s28, 64
	s_nop 0
	global_load_lds_dwordx4 v194, s[90:91]
	global_load_lds_dwordx4 v195, s[90:91] offset:1024
	global_load_lds_dwordx4 v196, s[90:91] offset:2048
	global_load_lds_dwordx4 v197, s[90:91] offset:3072
	s_add_u32 s90, s90, 64
	s_addc_u32 s91, s91, 0
